# down-proj consumers: the deferred-tile counter is loaded one iteration early (no blocking round trip at the poll), no wait after the invalidate
# baseline (speedup 1.0000x reference)
.LBB0_501:
	s_cmp_eq_u32 s2, 34
	s_cbranch_scc1 .Ldefer_chk
	s_cmp_eq_u32 s2, 36
	s_cbranch_scc0 .Ldefer_nowait
.Ldefer_chk:
	v_readlane_b32 s3, v255, 60
	s_cmp_eq_u32 s3, 0
	s_cbranch_scc1 .Ldefer_nowait
	v_readfirstlane_b32 s3, v225
	s_lshr_b32 s3, s3, 6
	s_cmp_eq_u32 s3, 0
	s_cbranch_scc0 .Ldefer_nowait
	s_load_dwordx2 s[76:77], s[0:1], 0xb0
	s_lshl_b32 s3, s18, 6
	s_add_i32 s3, s3, 0x3800
	s_waitcnt lgkmcnt(0)
	s_add_u32 s76, s76, s3
	s_addc_u32 s77, s77, 0
	s_cmp_eq_u32 s2, 34
	s_cbranch_scc0 .Ldefer_use
	global_load_dword v220, v1, s[76:77] sc1
	s_branch .Ldefer_nowait
.Ldefer_use:
	s_nop 0
	v_readfirstlane_b32 s3, v220
	s_cmp_ge_u32 s3, 32
	s_cbranch_scc1 .Ldefer_polled
.Ldefer_poll:
	global_load_dword v220, v1, s[76:77] sc1
	s_waitcnt vmcnt(0)
	v_readfirstlane_b32 s3, v220
	s_cmp_ge_u32 s3, 32
	s_cbranch_scc1 .Ldefer_polled
	s_sleep 1
	s_branch .Ldefer_poll
.Ldefer_polled:
	buffer_inv sc1
.Ldefer_nowait:
	s_add_i32 s76, s2, 2
	s_add_u32 s77, s42, 0x80
	s_addc_u32 s3, s43, 0
	s_add_i32 s80, 0, 0x10000
	s_cmp_eq_u32 s62, s2
	s_cselect_b32 s3, s37, s3
	s_cselect_b32 s2, s36, s77
	s_cselect_b32 s79, s39, s45
	s_cselect_b32 s78, s38, s44
	s_add_i32 s77, 0, 0x14000
	v_add_u32_e32 v70, s80, v182
	v_add_u32_e32 v94, s77, v182
	ds_read_b128 v[58:61], v70
	ds_read_b128 v[62:65], v70 offset:1024
	ds_read_b128 v[66:69], v70 offset:2048
	ds_read_b128 v[70:73], v70 offset:3072
	ds_read_b128 v[82:85], v94
	ds_read_b128 v[86:89], v94 offset:1024
	ds_read_b128 v[90:93], v94 offset:2048
	ds_read_b128 v[94:97], v94 offset:3072
	v_lshl_add_u64 v[180:181], s[42:43], 0, v[168:169]
	s_add_i32 m0, s48, 0xc000
	ds_read_b128 v[172:175], v183
	ds_read_b128 v[176:179], v183 offset:1024
	ds_read_b128 v[184:187], v183 offset:2048
	ds_read_b128 v[188:191], v183 offset:3072
	ds_read_b128 v[192:195], v183 offset:4096
	ds_read_b128 v[196:199], v183 offset:5120
	ds_read_b128 v[200:203], v183 offset:6144
	ds_read_b128 v[204:207], v183 offset:7168
	global_load_lds_dwordx4 v[180:181], off
	v_lshl_add_u64 v[180:181], s[42:43], 0, v[170:171]
	s_add_i32 m0, s48, 0xe000
	s_nop 0
	global_load_lds_dwordx4 v[180:181], off
	s_waitcnt vmcnt(8)
	s_waitcnt lgkmcnt(0)
	s_barrier
	s_setprio 1
	s_waitcnt lgkmcnt(0)
	v_mfma_f32_16x16x32_bf16 v[158:161], v[58:61], v[172:175], v[158:161]
	v_mfma_f32_16x16x32_bf16 v[154:157], v[66:69], v[172:175], v[154:157]
	v_mfma_f32_16x16x32_bf16 v[142:145], v[58:61], v[184:187], v[142:145]
	v_mfma_f32_16x16x32_bf16 v[138:141], v[66:69], v[184:187], v[138:141]
	v_mfma_f32_16x16x32_bf16 v[126:129], v[58:61], v[192:195], v[126:129]
	v_mfma_f32_16x16x32_bf16 v[122:125], v[66:69], v[192:195], v[122:125]
	v_mfma_f32_16x16x32_bf16 v[110:113], v[58:61], v[200:203], v[110:113]
	v_mfma_f32_16x16x32_bf16 v[106:109], v[66:69], v[200:203], v[106:109]
	v_mfma_f32_16x16x32_bf16 v[158:161], v[62:65], v[176:179], v[158:161]
	v_mfma_f32_16x16x32_bf16 v[154:157], v[70:73], v[176:179], v[154:157]
	v_mfma_f32_16x16x32_bf16 v[142:145], v[62:65], v[188:191], v[142:145]
	v_mfma_f32_16x16x32_bf16 v[138:141], v[70:73], v[188:191], v[138:141]
	v_mfma_f32_16x16x32_bf16 v[126:129], v[62:65], v[196:199], v[126:129]
	v_mfma_f32_16x16x32_bf16 v[122:125], v[70:73], v[196:199], v[122:125]
	v_mfma_f32_16x16x32_bf16 v[110:113], v[62:65], v[204:207], v[110:113]
	v_mfma_f32_16x16x32_bf16 v[106:109], v[70:73], v[204:207], v[106:109]
	s_setprio 0
	s_setprio 1
	v_mfma_f32_16x16x32_bf16 v[150:153], v[82:85], v[172:175], v[150:153]
	v_mfma_f32_16x16x32_bf16 v[146:149], v[90:93], v[172:175], v[146:149]
	v_mfma_f32_16x16x32_bf16 v[134:137], v[82:85], v[184:187], v[134:137]
	v_mfma_f32_16x16x32_bf16 v[130:133], v[90:93], v[184:187], v[130:133]
	v_mfma_f32_16x16x32_bf16 v[118:121], v[82:85], v[192:195], v[118:121]
	v_mfma_f32_16x16x32_bf16 v[114:117], v[90:93], v[192:195], v[114:117]
	v_mfma_f32_16x16x32_bf16 v[102:105], v[82:85], v[200:203], v[102:105]
	v_mfma_f32_16x16x32_bf16 v[98:101], v[90:93], v[200:203], v[98:101]
	v_mfma_f32_16x16x32_bf16 v[150:153], v[86:89], v[176:179], v[150:153]
	v_mfma_f32_16x16x32_bf16 v[146:149], v[94:97], v[176:179], v[146:149]
	v_mfma_f32_16x16x32_bf16 v[134:137], v[86:89], v[188:191], v[134:137]
	v_mfma_f32_16x16x32_bf16 v[130:133], v[94:97], v[188:191], v[130:133]
	v_mfma_f32_16x16x32_bf16 v[118:121], v[86:89], v[196:199], v[118:121]
	v_mfma_f32_16x16x32_bf16 v[114:117], v[94:97], v[196:199], v[114:117]
	v_mfma_f32_16x16x32_bf16 v[102:105], v[86:89], v[204:207], v[102:105]
	v_mfma_f32_16x16x32_bf16 v[98:101], v[94:97], v[204:207], v[98:101]
	s_setprio 0
	s_barrier
	s_add_i32 s80, s80, s13
	v_lshl_add_u64 v[180:181], s[78:79], 0, v[0:1]
	s_mov_b32 m0, s80
	ds_read_b128 v[172:175], v183 offset:16384
	ds_read_b128 v[176:179], v183 offset:17408
	ds_read_b128 v[184:187], v183 offset:18432
	ds_read_b128 v[188:191], v183 offset:19456
	ds_read_b128 v[192:195], v183 offset:20480
	ds_read_b128 v[196:199], v183 offset:21504
	ds_read_b128 v[200:203], v183 offset:22528
	ds_read_b128 v[204:207], v183 offset:23552
	global_load_lds_dwordx4 v[180:181], off
	s_add_i32 m0, s80, 0x2000
	v_lshl_add_u64 v[208:209], s[78:79], 0, v[166:167]
	s_add_u32 s78, s78, s54
	s_addc_u32 s79, s79, 0
	s_add_i32 s77, s77, s13
	global_load_lds_dwordx4 v[208:209], off
	v_lshl_add_u64 v[210:211], s[78:79], 0, v[0:1]
	s_mov_b32 m0, s77
	v_lshl_add_u64 v[212:213], s[78:79], 0, v[166:167]
	global_load_lds_dwordx4 v[210:211], off
	s_add_i32 m0, s77, 0x2000
	v_lshl_add_u64 v[214:215], s[2:3], 0, v[162:163]
	global_load_lds_dwordx4 v[212:213], off
	s_mov_b32 m0, s48
	v_lshl_add_u64 v[216:217], s[2:3], 0, v[164:165]
	global_load_lds_dwordx4 v[214:215], off
	s_mov_b32 m0, s49
	s_nop 0
	global_load_lds_dwordx4 v[216:217], off
	s_waitcnt vmcnt(8)
	s_waitcnt lgkmcnt(0)
	s_barrier
	s_setprio 1
	s_waitcnt lgkmcnt(0)
	v_mfma_f32_16x16x32_bf16 v[78:81], v[58:61], v[172:175], v[78:81]
	v_mfma_f32_16x16x32_bf16 v[74:77], v[66:69], v[172:175], v[74:77]
	v_mfma_f32_16x16x32_bf16 v[46:49], v[58:61], v[184:187], v[46:49]
	v_mfma_f32_16x16x32_bf16 v[42:45], v[66:69], v[184:187], v[42:45]
	v_mfma_f32_16x16x32_bf16 v[30:33], v[58:61], v[192:195], v[30:33]
	v_mfma_f32_16x16x32_bf16 v[26:29], v[66:69], v[192:195], v[26:29]
	v_mfma_f32_16x16x32_bf16 v[14:17], v[58:61], v[200:203], v[14:17]
	v_mfma_f32_16x16x32_bf16 v[10:13], v[66:69], v[200:203], v[10:13]
	v_mfma_f32_16x16x32_bf16 v[78:81], v[62:65], v[176:179], v[78:81]
	v_mfma_f32_16x16x32_bf16 v[74:77], v[70:73], v[176:179], v[74:77]
	v_mfma_f32_16x16x32_bf16 v[46:49], v[62:65], v[188:191], v[46:49]
	v_mfma_f32_16x16x32_bf16 v[42:45], v[70:73], v[188:191], v[42:45]
	v_mfma_f32_16x16x32_bf16 v[30:33], v[62:65], v[196:199], v[30:33]
	v_mfma_f32_16x16x32_bf16 v[26:29], v[70:73], v[196:199], v[26:29]
	v_mfma_f32_16x16x32_bf16 v[14:17], v[62:65], v[204:207], v[14:17]
	v_mfma_f32_16x16x32_bf16 v[10:13], v[70:73], v[204:207], v[10:13]
	s_setprio 0
	s_setprio 1
	v_mfma_f32_16x16x32_bf16 v[54:57], v[82:85], v[172:175], v[54:57]
	v_mfma_f32_16x16x32_bf16 v[50:53], v[90:93], v[172:175], v[50:53]
	v_mfma_f32_16x16x32_bf16 v[38:41], v[82:85], v[184:187], v[38:41]
	v_mfma_f32_16x16x32_bf16 v[34:37], v[90:93], v[184:187], v[34:37]
	v_mfma_f32_16x16x32_bf16 v[22:25], v[82:85], v[192:195], v[22:25]
	v_mfma_f32_16x16x32_bf16 v[18:21], v[90:93], v[192:195], v[18:21]
	v_mfma_f32_16x16x32_bf16 v[6:9], v[82:85], v[200:203], v[6:9]
	v_mfma_f32_16x16x32_bf16 v[2:5], v[90:93], v[200:203], v[2:5]
	v_mfma_f32_16x16x32_bf16 v[54:57], v[86:89], v[176:179], v[54:57]
	v_mfma_f32_16x16x32_bf16 v[50:53], v[94:97], v[176:179], v[50:53]
	v_mfma_f32_16x16x32_bf16 v[38:41], v[86:89], v[188:191], v[38:41]
	v_mfma_f32_16x16x32_bf16 v[34:37], v[94:97], v[188:191], v[34:37]
	v_mfma_f32_16x16x32_bf16 v[22:25], v[86:89], v[196:199], v[22:25]
	v_mfma_f32_16x16x32_bf16 v[18:21], v[94:97], v[196:199], v[18:21]
	v_mfma_f32_16x16x32_bf16 v[6:9], v[86:89], v[204:207], v[6:9]
	v_mfma_f32_16x16x32_bf16 v[2:5], v[94:97], v[204:207], v[2:5]
	s_setprio 0
	s_barrier
	s_add_i32 s77, 0, 0x18000
	s_add_i32 s78, 0, 0x1c000
	v_add_u32_e32 v70, s77, v182
	v_add_u32_e32 v94, s78, v182
	ds_read_b128 v[58:61], v70
	ds_read_b128 v[62:65], v70 offset:1024
	ds_read_b128 v[66:69], v70 offset:2048
	ds_read_b128 v[70:73], v70 offset:3072
	ds_read_b128 v[82:85], v94
	ds_read_b128 v[86:89], v94 offset:1024
	ds_read_b128 v[90:93], v94 offset:2048
	ds_read_b128 v[94:97], v94 offset:3072
	s_add_u32 s2, s2, s54
	s_addc_u32 s3, s3, 0
	s_mov_b32 m0, s50
	v_lshl_add_u64 v[218:219], s[2:3], 0, v[162:163]
	ds_read_b128 v[172:175], v183 offset:32768
	ds_read_b128 v[176:179], v183 offset:33792
	ds_read_b128 v[184:187], v183 offset:34816
	ds_read_b128 v[188:191], v183 offset:35840
	ds_read_b128 v[192:195], v183 offset:36864
	ds_read_b128 v[196:199], v183 offset:37888
	ds_read_b128 v[200:203], v183 offset:38912
	ds_read_b128 v[204:207], v183 offset:39936
	global_load_lds_dwordx4 v[218:219], off
	v_lshl_add_u64 v[218:219], s[2:3], 0, v[164:165]
	s_mov_b32 m0, s51
	s_nop 0
	global_load_lds_dwordx4 v[218:219], off
	s_waitcnt vmcnt(8)
	s_waitcnt lgkmcnt(0)
	s_barrier
	s_setprio 1
	s_waitcnt lgkmcnt(0)
	v_mfma_f32_16x16x32_bf16 v[158:161], v[58:61], v[172:175], v[158:161]
	v_mfma_f32_16x16x32_bf16 v[154:157], v[66:69], v[172:175], v[154:157]
	v_mfma_f32_16x16x32_bf16 v[142:145], v[58:61], v[184:187], v[142:145]
	v_mfma_f32_16x16x32_bf16 v[138:141], v[66:69], v[184:187], v[138:141]
	v_mfma_f32_16x16x32_bf16 v[126:129], v[58:61], v[192:195], v[126:129]
	v_mfma_f32_16x16x32_bf16 v[122:125], v[66:69], v[192:195], v[122:125]
	v_mfma_f32_16x16x32_bf16 v[110:113], v[58:61], v[200:203], v[110:113]
	v_mfma_f32_16x16x32_bf16 v[106:109], v[66:69], v[200:203], v[106:109]
	v_mfma_f32_16x16x32_bf16 v[158:161], v[62:65], v[176:179], v[158:161]
	v_mfma_f32_16x16x32_bf16 v[154:157], v[70:73], v[176:179], v[154:157]
	v_mfma_f32_16x16x32_bf16 v[142:145], v[62:65], v[188:191], v[142:145]
	v_mfma_f32_16x16x32_bf16 v[138:141], v[70:73], v[188:191], v[138:141]
	v_mfma_f32_16x16x32_bf16 v[126:129], v[62:65], v[196:199], v[126:129]
	v_mfma_f32_16x16x32_bf16 v[122:125], v[70:73], v[196:199], v[122:125]
	v_mfma_f32_16x16x32_bf16 v[110:113], v[62:65], v[204:207], v[110:113]
	v_mfma_f32_16x16x32_bf16 v[106:109], v[70:73], v[204:207], v[106:109]
	s_setprio 0
	s_setprio 1
	v_mfma_f32_16x16x32_bf16 v[150:153], v[82:85], v[172:175], v[150:153]
	v_mfma_f32_16x16x32_bf16 v[146:149], v[90:93], v[172:175], v[146:149]
	v_mfma_f32_16x16x32_bf16 v[134:137], v[82:85], v[184:187], v[134:137]
	v_mfma_f32_16x16x32_bf16 v[130:133], v[90:93], v[184:187], v[130:133]
	v_mfma_f32_16x16x32_bf16 v[118:121], v[82:85], v[192:195], v[118:121]
	v_mfma_f32_16x16x32_bf16 v[114:117], v[90:93], v[192:195], v[114:117]
	v_mfma_f32_16x16x32_bf16 v[102:105], v[82:85], v[200:203], v[102:105]
	v_mfma_f32_16x16x32_bf16 v[98:101], v[90:93], v[200:203], v[98:101]
	v_mfma_f32_16x16x32_bf16 v[150:153], v[86:89], v[176:179], v[150:153]
	v_mfma_f32_16x16x32_bf16 v[146:149], v[94:97], v[176:179], v[146:149]
	v_mfma_f32_16x16x32_bf16 v[134:137], v[86:89], v[188:191], v[134:137]
	v_mfma_f32_16x16x32_bf16 v[130:133], v[94:97], v[188:191], v[130:133]
	v_mfma_f32_16x16x32_bf16 v[118:121], v[86:89], v[196:199], v[118:121]
	v_mfma_f32_16x16x32_bf16 v[114:117], v[94:97], v[196:199], v[114:117]
	v_mfma_f32_16x16x32_bf16 v[102:105], v[86:89], v[204:207], v[102:105]
	v_mfma_f32_16x16x32_bf16 v[98:101], v[94:97], v[204:207], v[98:101]
	s_setprio 0
	s_barrier
	s_add_i32 s2, s77, s13
	v_lshl_add_u64 v[180:181], v[180:181], 0, s[8:9]
	s_mov_b32 m0, s2
	ds_read_b128 v[172:175], v183 offset:49152
	ds_read_b128 v[176:179], v183 offset:50176
	ds_read_b128 v[184:187], v183 offset:51200
	ds_read_b128 v[188:191], v183 offset:52224
	ds_read_b128 v[192:195], v183 offset:53248
	ds_read_b128 v[196:199], v183 offset:54272
	ds_read_b128 v[200:203], v183 offset:55296
	ds_read_b128 v[204:207], v183 offset:56320
	global_load_lds_dwordx4 v[180:181], off
	v_lshl_add_u64 v[180:181], v[208:209], 0, s[8:9]
	s_add_i32 m0, s2, 0x2000
	s_add_i32 s2, s78, s13
	global_load_lds_dwordx4 v[180:181], off
	v_lshl_add_u64 v[180:181], v[210:211], 0, s[8:9]
	s_mov_b32 m0, s2
	s_nop 0
	global_load_lds_dwordx4 v[180:181], off
	v_lshl_add_u64 v[180:181], v[212:213], 0, s[8:9]
	s_add_i32 m0, s2, 0x2000
	s_nop 0
	global_load_lds_dwordx4 v[180:181], off
	v_lshl_add_u64 v[180:181], v[214:215], 0, s[8:9]
	s_mov_b32 m0, s60
	s_nop 0
	global_load_lds_dwordx4 v[180:181], off
	v_lshl_add_u64 v[180:181], v[216:217], 0, s[8:9]
	s_mov_b32 m0, s61
	s_nop 0
	global_load_lds_dwordx4 v[180:181], off
	s_waitcnt vmcnt(8)
	s_waitcnt lgkmcnt(0)
	s_barrier
	s_setprio 1
	s_waitcnt lgkmcnt(0)
	v_mfma_f32_16x16x32_bf16 v[78:81], v[58:61], v[172:175], v[78:81]
	v_mfma_f32_16x16x32_bf16 v[74:77], v[66:69], v[172:175], v[74:77]
	v_mfma_f32_16x16x32_bf16 v[46:49], v[58:61], v[184:187], v[46:49]
	v_mfma_f32_16x16x32_bf16 v[42:45], v[66:69], v[184:187], v[42:45]
	v_mfma_f32_16x16x32_bf16 v[30:33], v[58:61], v[192:195], v[30:33]
	v_mfma_f32_16x16x32_bf16 v[26:29], v[66:69], v[192:195], v[26:29]
	v_mfma_f32_16x16x32_bf16 v[14:17], v[58:61], v[200:203], v[14:17]
	v_mfma_f32_16x16x32_bf16 v[10:13], v[66:69], v[200:203], v[10:13]
	v_mfma_f32_16x16x32_bf16 v[78:81], v[62:65], v[176:179], v[78:81]
	v_mfma_f32_16x16x32_bf16 v[74:77], v[70:73], v[176:179], v[74:77]
	v_mfma_f32_16x16x32_bf16 v[46:49], v[62:65], v[188:191], v[46:49]
	v_mfma_f32_16x16x32_bf16 v[42:45], v[70:73], v[188:191], v[42:45]
	v_mfma_f32_16x16x32_bf16 v[30:33], v[62:65], v[196:199], v[30:33]
	v_mfma_f32_16x16x32_bf16 v[26:29], v[70:73], v[196:199], v[26:29]
	v_mfma_f32_16x16x32_bf16 v[14:17], v[62:65], v[204:207], v[14:17]
	v_mfma_f32_16x16x32_bf16 v[10:13], v[70:73], v[204:207], v[10:13]
	s_setprio 0
	s_setprio 1
	v_mfma_f32_16x16x32_bf16 v[54:57], v[82:85], v[172:175], v[54:57]
	v_mfma_f32_16x16x32_bf16 v[50:53], v[90:93], v[172:175], v[50:53]
	v_mfma_f32_16x16x32_bf16 v[38:41], v[82:85], v[184:187], v[38:41]
	v_mfma_f32_16x16x32_bf16 v[34:37], v[90:93], v[184:187], v[34:37]
	v_mfma_f32_16x16x32_bf16 v[22:25], v[82:85], v[192:195], v[22:25]
	v_mfma_f32_16x16x32_bf16 v[18:21], v[90:93], v[192:195], v[18:21]
	v_mfma_f32_16x16x32_bf16 v[6:9], v[82:85], v[200:203], v[6:9]
	v_mfma_f32_16x16x32_bf16 v[2:5], v[90:93], v[200:203], v[2:5]
	v_mfma_f32_16x16x32_bf16 v[54:57], v[86:89], v[176:179], v[54:57]
	v_mfma_f32_16x16x32_bf16 v[50:53], v[94:97], v[176:179], v[50:53]
	v_mfma_f32_16x16x32_bf16 v[38:41], v[86:89], v[188:191], v[38:41]
	v_mfma_f32_16x16x32_bf16 v[34:37], v[94:97], v[188:191], v[34:37]
	v_mfma_f32_16x16x32_bf16 v[22:25], v[86:89], v[196:199], v[22:25]
	v_mfma_f32_16x16x32_bf16 v[18:21], v[94:97], v[196:199], v[18:21]
	v_mfma_f32_16x16x32_bf16 v[6:9], v[86:89], v[204:207], v[6:9]
	v_mfma_f32_16x16x32_bf16 v[2:5], v[94:97], v[204:207], v[2:5]
	s_setprio 0
	s_barrier
	s_add_u32 s42, s42, 0x100
	s_addc_u32 s43, s43, 0
	s_add_u32 s44, s44, 0x100
	s_addc_u32 s45, s45, 0
	s_cmp_ge_u32 s76, s15
	s_mov_b32 s2, s76
	s_cbranch_scc0 .LBB0_501
	s_and_b64 vcc, exec, s[24:25]
	s_cbranch_vccz .LBB0_504
	s_barrier
